# grid barrier: drop the unused per-XCD generation bump in the leader path
# speedup vs baseline: 1.0245x; 1.0014x over previous
.LBB0_1965:
	s_or_b64 exec, exec, s[2:3]
	s_mov_b64 s[2:3], exec
	v_mbcnt_lo_u32_b32 v0, s2, 0
	v_mbcnt_hi_u32_b32 v0, s3, v0
	v_cmp_eq_u32_e32 vcc, 0, v0
	s_waitcnt vmcnt(0)
	buffer_inv sc1
	s_and_saveexec_b64 s[4:5], vcc
	s_cbranch_execz .LBB0_1967
	s_bcnt1_i32_b64 s2, s[2:3]
	v_mov_b32_e32 v0, s2
	v_readlane_b32 s2, v254, 25
	v_readlane_b32 s3, v254, 26
	s_nop 4
.LBB0_1967:
	s_or_b64 exec, exec, s[4:5]
	s_waitcnt vmcnt(0)
